# GEMM K-loops (in-proj/out-proj/gate-up): 9 of 10 m0-hazard s_nops per iteration replaced by existing SALU (pointer/constant updates moved into the slots)
# speedup vs baseline: 1.0053x; 1.0053x over previous
.LBB0_169:
	s_add_u32 s42, s40, 0xfff80080
	s_addc_u32 s43, s41, -1
	s_add_i32 s52, 0, 0x10000
	s_cmp_eq_u32 s51, 28
	s_cselect_b32 s45, s13, s43
	s_cselect_b32 s44, s47, s42
	s_cselect_b32 s43, s11, s50
	s_cselect_b32 s42, s48, s49
	ds_read_b128 v[130:133], v236
	ds_read_b128 v[134:137], v236 offset:1024
	ds_read_b128 v[138:141], v236 offset:2048
	ds_read_b128 v[142:145], v236 offset:3072
	ds_read_b128 v[170:173], v237
	ds_read_b128 v[184:187], v237 offset:1024
	ds_read_b128 v[188:191], v237 offset:2048
	ds_read_b128 v[192:195], v237 offset:3072
	s_add_i32 m0, s14, 0xc000
	ds_read_b128 v[196:199], v183
	ds_read_b128 v[200:203], v183 offset:1024
	ds_read_b128 v[210:213], v183 offset:2048
	ds_read_b128 v[214:217], v183 offset:3072
	ds_read_b128 v[218:221], v183 offset:4096
	ds_read_b128 v[222:225], v183 offset:5120
	ds_read_b128 v[226:229], v183 offset:6144
	ds_read_b128 v[230:233], v183 offset:7168
	global_load_lds_dwordx4 v166, s[40:41]
	s_add_i32 m0, s14, 0xe000
	s_add_i32 s54, 0, 0x14000
	global_load_lds_dwordx4 v168, s[40:41]
	s_waitcnt vmcnt(8) lgkmcnt(0)
	s_barrier
	v_mfma_f32_16x16x32_bf16 v[126:129], v[130:133], v[196:199], v[126:129]
	v_mfma_f32_16x16x32_bf16 v[122:125], v[138:141], v[196:199], v[122:125]
	v_mfma_f32_16x16x32_bf16 v[118:121], v[130:133], v[210:213], v[118:121]
	v_mfma_f32_16x16x32_bf16 v[110:113], v[138:141], v[210:213], v[110:113]
	v_mfma_f32_16x16x32_bf16 v[102:105], v[130:133], v[218:221], v[102:105]
	v_mfma_f32_16x16x32_bf16 v[94:97], v[138:141], v[218:221], v[94:97]
	v_mfma_f32_16x16x32_bf16 v[86:89], v[130:133], v[226:229], v[86:89]
	v_mfma_f32_16x16x32_bf16 v[78:81], v[138:141], v[226:229], v[78:81]
	v_mfma_f32_16x16x32_bf16 v[126:129], v[134:137], v[200:203], v[126:129]
	v_mfma_f32_16x16x32_bf16 v[122:125], v[142:145], v[200:203], v[122:125]
	v_mfma_f32_16x16x32_bf16 v[118:121], v[134:137], v[214:217], v[118:121]
	v_mfma_f32_16x16x32_bf16 v[110:113], v[142:145], v[214:217], v[110:113]
	v_mfma_f32_16x16x32_bf16 v[102:105], v[134:137], v[222:225], v[102:105]
	v_mfma_f32_16x16x32_bf16 v[94:97], v[142:145], v[222:225], v[94:97]
	v_mfma_f32_16x16x32_bf16 v[86:89], v[134:137], v[230:233], v[86:89]
	v_mfma_f32_16x16x32_bf16 v[78:81], v[142:145], v[230:233], v[78:81]
	v_mfma_f32_16x16x32_bf16 v[114:117], v[170:173], v[196:199], v[114:117]
	v_mfma_f32_16x16x32_bf16 v[106:109], v[188:191], v[196:199], v[106:109]
	v_mfma_f32_16x16x32_bf16 v[98:101], v[170:173], v[210:213], v[98:101]
	v_mfma_f32_16x16x32_bf16 v[90:93], v[188:191], v[210:213], v[90:93]
	v_mfma_f32_16x16x32_bf16 v[82:85], v[170:173], v[218:221], v[82:85]
	v_mfma_f32_16x16x32_bf16 v[74:77], v[188:191], v[218:221], v[74:77]
	v_mfma_f32_16x16x32_bf16 v[70:73], v[170:173], v[226:229], v[70:73]
	v_mfma_f32_16x16x32_bf16 v[66:69], v[188:191], v[226:229], v[66:69]
	v_mfma_f32_16x16x32_bf16 v[114:117], v[184:187], v[200:203], v[114:117]
	v_mfma_f32_16x16x32_bf16 v[106:109], v[192:195], v[200:203], v[106:109]
	v_mfma_f32_16x16x32_bf16 v[98:101], v[184:187], v[214:217], v[98:101]
	v_mfma_f32_16x16x32_bf16 v[90:93], v[192:195], v[214:217], v[90:93]
	v_mfma_f32_16x16x32_bf16 v[82:85], v[184:187], v[222:225], v[82:85]
	v_mfma_f32_16x16x32_bf16 v[74:77], v[192:195], v[222:225], v[74:77]
	v_mfma_f32_16x16x32_bf16 v[70:73], v[184:187], v[230:233], v[70:73]
	v_mfma_f32_16x16x32_bf16 v[66:69], v[192:195], v[230:233], v[66:69]
	s_barrier
	s_add_i32 s52, s52, s5
	s_mov_b32 m0, s52
	ds_read_b128 v[196:199], v183 offset:16384
	ds_read_b128 v[200:203], v183 offset:17408
	ds_read_b128 v[210:213], v183 offset:18432
	ds_read_b128 v[214:217], v183 offset:19456
	ds_read_b128 v[218:221], v183 offset:20480
	ds_read_b128 v[222:225], v183 offset:21504
	ds_read_b128 v[226:229], v183 offset:22528
	ds_read_b128 v[230:233], v183 offset:23552
	global_load_lds_dwordx4 v162, s[42:43]
	s_add_i32 m0, s52, 0x2000
	s_add_i32 s54, s54, s5
	global_load_lds_dwordx4 v158, s[42:43]
	s_mov_b32 m0, s54
	s_add_u32 s52, s42, 0x80000
	s_addc_u32 s53, s43, 0
	global_load_lds_dwordx4 v162, s[52:53]
	s_add_i32 m0, s54, 0x2000
	s_add_u32 s100, s44, 0x80
	global_load_lds_dwordx4 v158, s[52:53]
	s_addc_u32 s101, s45, 0
	s_mov_b32 m0, s14
	s_add_u32 s98, s42, 0x80
	global_load_lds_dwordx4 v164, s[44:45]
	s_mov_b32 m0, s15
	s_addc_u32 s99, s43, 0
	global_load_lds_dwordx4 v160, s[44:45]
	s_waitcnt vmcnt(8) lgkmcnt(0)
	s_barrier
	v_mfma_f32_16x16x32_bf16 v[62:65], v[130:133], v[196:199], v[62:65]
	v_mfma_f32_16x16x32_bf16 v[58:61], v[138:141], v[196:199], v[58:61]
	v_mfma_f32_16x16x32_bf16 v[54:57], v[130:133], v[210:213], v[54:57]
	v_mfma_f32_16x16x32_bf16 v[46:49], v[138:141], v[210:213], v[46:49]
	v_mfma_f32_16x16x32_bf16 v[38:41], v[130:133], v[218:221], v[38:41]
	v_mfma_f32_16x16x32_bf16 v[30:33], v[138:141], v[218:221], v[30:33]
	v_mfma_f32_16x16x32_bf16 v[22:25], v[130:133], v[226:229], v[22:25]
	v_mfma_f32_16x16x32_bf16 v[14:17], v[138:141], v[226:229], v[14:17]
	v_mfma_f32_16x16x32_bf16 v[62:65], v[134:137], v[200:203], v[62:65]
	v_mfma_f32_16x16x32_bf16 v[58:61], v[142:145], v[200:203], v[58:61]
	v_mfma_f32_16x16x32_bf16 v[54:57], v[134:137], v[214:217], v[54:57]
	v_mfma_f32_16x16x32_bf16 v[46:49], v[142:145], v[214:217], v[46:49]
	v_mfma_f32_16x16x32_bf16 v[38:41], v[134:137], v[222:225], v[38:41]
	v_mfma_f32_16x16x32_bf16 v[30:33], v[142:145], v[222:225], v[30:33]
	v_mfma_f32_16x16x32_bf16 v[22:25], v[134:137], v[230:233], v[22:25]
	v_mfma_f32_16x16x32_bf16 v[14:17], v[142:145], v[230:233], v[14:17]
	v_mfma_f32_16x16x32_bf16 v[50:53], v[170:173], v[196:199], v[50:53]
	v_mfma_f32_16x16x32_bf16 v[42:45], v[188:191], v[196:199], v[42:45]
	v_mfma_f32_16x16x32_bf16 v[34:37], v[170:173], v[210:213], v[34:37]
	v_mfma_f32_16x16x32_bf16 v[26:29], v[188:191], v[210:213], v[26:29]
	v_mfma_f32_16x16x32_bf16 v[18:21], v[170:173], v[218:221], v[18:21]
	v_mfma_f32_16x16x32_bf16 v[10:13], v[188:191], v[218:221], v[10:13]
	v_mfma_f32_16x16x32_bf16 v[6:9], v[170:173], v[226:229], v[6:9]
	v_mfma_f32_16x16x32_bf16 v[2:5], v[188:191], v[226:229], v[2:5]
	v_mfma_f32_16x16x32_bf16 v[50:53], v[184:187], v[200:203], v[50:53]
	v_mfma_f32_16x16x32_bf16 v[42:45], v[192:195], v[200:203], v[42:45]
	v_mfma_f32_16x16x32_bf16 v[34:37], v[184:187], v[214:217], v[34:37]
	v_mfma_f32_16x16x32_bf16 v[26:29], v[192:195], v[214:217], v[26:29]
	v_mfma_f32_16x16x32_bf16 v[18:21], v[184:187], v[222:225], v[18:21]
	v_mfma_f32_16x16x32_bf16 v[10:13], v[192:195], v[222:225], v[10:13]
	v_mfma_f32_16x16x32_bf16 v[6:9], v[184:187], v[230:233], v[6:9]
	v_mfma_f32_16x16x32_bf16 v[2:5], v[192:195], v[230:233], v[2:5]
	s_barrier
	s_add_i32 s52, 0, 0x18000
	ds_read_b128 v[130:133], v238
	ds_read_b128 v[134:137], v238 offset:1024
	ds_read_b128 v[138:141], v238 offset:2048
	ds_read_b128 v[142:145], v238 offset:3072
	ds_read_b128 v[170:173], v239
	ds_read_b128 v[184:187], v239 offset:1024
	ds_read_b128 v[188:191], v239 offset:2048
	ds_read_b128 v[192:195], v239 offset:3072
	s_add_u32 s44, s44, 0x80000
	s_addc_u32 s45, s45, 0
	s_mov_b32 m0, s16
	ds_read_b128 v[196:199], v183 offset:32768
	ds_read_b128 v[200:203], v183 offset:33792
	ds_read_b128 v[210:213], v183 offset:34816
	ds_read_b128 v[214:217], v183 offset:35840
	ds_read_b128 v[218:221], v183 offset:36864
	ds_read_b128 v[222:225], v183 offset:37888
	ds_read_b128 v[226:229], v183 offset:38912
	ds_read_b128 v[230:233], v183 offset:39936
	global_load_lds_dwordx4 v164, s[44:45]
	s_mov_b32 m0, s18
	s_add_i32 s53, 0, 0x1c000
	global_load_lds_dwordx4 v160, s[44:45]
	s_waitcnt vmcnt(8) lgkmcnt(0)
	s_barrier
	v_mfma_f32_16x16x32_bf16 v[126:129], v[130:133], v[196:199], v[126:129]
	v_mfma_f32_16x16x32_bf16 v[122:125], v[138:141], v[196:199], v[122:125]
	v_mfma_f32_16x16x32_bf16 v[118:121], v[130:133], v[210:213], v[118:121]
	v_mfma_f32_16x16x32_bf16 v[110:113], v[138:141], v[210:213], v[110:113]
	v_mfma_f32_16x16x32_bf16 v[102:105], v[130:133], v[218:221], v[102:105]
	v_mfma_f32_16x16x32_bf16 v[94:97], v[138:141], v[218:221], v[94:97]
	v_mfma_f32_16x16x32_bf16 v[86:89], v[130:133], v[226:229], v[86:89]
	v_mfma_f32_16x16x32_bf16 v[78:81], v[138:141], v[226:229], v[78:81]
	v_mfma_f32_16x16x32_bf16 v[126:129], v[134:137], v[200:203], v[126:129]
	v_mfma_f32_16x16x32_bf16 v[122:125], v[142:145], v[200:203], v[122:125]
	v_mfma_f32_16x16x32_bf16 v[118:121], v[134:137], v[214:217], v[118:121]
	v_mfma_f32_16x16x32_bf16 v[110:113], v[142:145], v[214:217], v[110:113]
	v_mfma_f32_16x16x32_bf16 v[102:105], v[134:137], v[222:225], v[102:105]
	v_mfma_f32_16x16x32_bf16 v[94:97], v[142:145], v[222:225], v[94:97]
	v_mfma_f32_16x16x32_bf16 v[86:89], v[134:137], v[230:233], v[86:89]
	v_mfma_f32_16x16x32_bf16 v[78:81], v[142:145], v[230:233], v[78:81]
	v_mfma_f32_16x16x32_bf16 v[114:117], v[170:173], v[196:199], v[114:117]
	v_mfma_f32_16x16x32_bf16 v[106:109], v[188:191], v[196:199], v[106:109]
	v_mfma_f32_16x16x32_bf16 v[98:101], v[170:173], v[210:213], v[98:101]
	v_mfma_f32_16x16x32_bf16 v[90:93], v[188:191], v[210:213], v[90:93]
	v_mfma_f32_16x16x32_bf16 v[82:85], v[170:173], v[218:221], v[82:85]
	v_mfma_f32_16x16x32_bf16 v[74:77], v[188:191], v[218:221], v[74:77]
	v_mfma_f32_16x16x32_bf16 v[70:73], v[170:173], v[226:229], v[70:73]
	v_mfma_f32_16x16x32_bf16 v[66:69], v[188:191], v[226:229], v[66:69]
	v_mfma_f32_16x16x32_bf16 v[114:117], v[184:187], v[200:203], v[114:117]
	v_mfma_f32_16x16x32_bf16 v[106:109], v[192:195], v[200:203], v[106:109]
	v_mfma_f32_16x16x32_bf16 v[98:101], v[184:187], v[214:217], v[98:101]
	v_mfma_f32_16x16x32_bf16 v[90:93], v[192:195], v[214:217], v[90:93]
	v_mfma_f32_16x16x32_bf16 v[82:85], v[184:187], v[222:225], v[82:85]
	v_mfma_f32_16x16x32_bf16 v[74:77], v[192:195], v[222:225], v[74:77]
	v_mfma_f32_16x16x32_bf16 v[70:73], v[184:187], v[230:233], v[70:73]
	v_mfma_f32_16x16x32_bf16 v[66:69], v[192:195], v[230:233], v[66:69]
	s_barrier
	s_add_i32 s44, s52, s5
	s_mov_b32 m0, s44
	ds_read_b128 v[196:199], v183 offset:49152
	ds_read_b128 v[200:203], v183 offset:50176
	ds_read_b128 v[210:213], v183 offset:51200
	ds_read_b128 v[214:217], v183 offset:52224
	ds_read_b128 v[218:221], v183 offset:53248
	ds_read_b128 v[222:225], v183 offset:54272
	ds_read_b128 v[226:229], v183 offset:55296
	ds_read_b128 v[230:233], v183 offset:56320
	global_load_lds_dwordx4 v162, s[98:99]
	s_add_i32 m0, s44, 0x2000
	s_add_i32 s44, s53, s5
	global_load_lds_dwordx4 v158, s[98:99]
	s_mov_b32 m0, s44
	s_add_u32 s42, s42, 0x80080
	s_addc_u32 s43, s43, 0
	global_load_lds_dwordx4 v162, s[42:43]
	s_add_i32 m0, s44, 0x2000
	s_nop 0
	global_load_lds_dwordx4 v158, s[42:43]
	s_mov_b32 m0, s19
	s_add_u32 s40, s40, 0x100
	global_load_lds_dwordx4 v164, s[100:101]
	s_mov_b32 m0, s25
	s_addc_u32 s41, s41, 0
	global_load_lds_dwordx4 v160, s[100:101]
	s_waitcnt vmcnt(8) lgkmcnt(0)
	s_barrier
	v_mfma_f32_16x16x32_bf16 v[62:65], v[130:133], v[196:199], v[62:65]
	v_mfma_f32_16x16x32_bf16 v[58:61], v[138:141], v[196:199], v[58:61]
	v_mfma_f32_16x16x32_bf16 v[54:57], v[130:133], v[210:213], v[54:57]
	v_mfma_f32_16x16x32_bf16 v[46:49], v[138:141], v[210:213], v[46:49]
	v_mfma_f32_16x16x32_bf16 v[38:41], v[130:133], v[218:221], v[38:41]
	v_mfma_f32_16x16x32_bf16 v[30:33], v[138:141], v[218:221], v[30:33]
	v_mfma_f32_16x16x32_bf16 v[22:25], v[130:133], v[226:229], v[22:25]
	v_mfma_f32_16x16x32_bf16 v[14:17], v[138:141], v[226:229], v[14:17]
	v_mfma_f32_16x16x32_bf16 v[62:65], v[134:137], v[200:203], v[62:65]
	v_mfma_f32_16x16x32_bf16 v[58:61], v[142:145], v[200:203], v[58:61]
	v_mfma_f32_16x16x32_bf16 v[54:57], v[134:137], v[214:217], v[54:57]
	v_mfma_f32_16x16x32_bf16 v[46:49], v[142:145], v[214:217], v[46:49]
	v_mfma_f32_16x16x32_bf16 v[38:41], v[134:137], v[222:225], v[38:41]
	v_mfma_f32_16x16x32_bf16 v[30:33], v[142:145], v[222:225], v[30:33]
	v_mfma_f32_16x16x32_bf16 v[22:25], v[134:137], v[230:233], v[22:25]
	v_mfma_f32_16x16x32_bf16 v[14:17], v[142:145], v[230:233], v[14:17]
	v_mfma_f32_16x16x32_bf16 v[50:53], v[170:173], v[196:199], v[50:53]
	v_mfma_f32_16x16x32_bf16 v[42:45], v[188:191], v[196:199], v[42:45]
	v_mfma_f32_16x16x32_bf16 v[34:37], v[170:173], v[210:213], v[34:37]
	v_mfma_f32_16x16x32_bf16 v[26:29], v[188:191], v[210:213], v[26:29]
	v_mfma_f32_16x16x32_bf16 v[18:21], v[170:173], v[218:221], v[18:21]
	v_mfma_f32_16x16x32_bf16 v[10:13], v[188:191], v[218:221], v[10:13]
	v_mfma_f32_16x16x32_bf16 v[6:9], v[170:173], v[226:229], v[6:9]
	v_mfma_f32_16x16x32_bf16 v[2:5], v[188:191], v[226:229], v[2:5]
	v_mfma_f32_16x16x32_bf16 v[50:53], v[184:187], v[200:203], v[50:53]
	v_mfma_f32_16x16x32_bf16 v[42:45], v[192:195], v[200:203], v[42:45]
	v_mfma_f32_16x16x32_bf16 v[34:37], v[184:187], v[214:217], v[34:37]
	v_mfma_f32_16x16x32_bf16 v[26:29], v[192:195], v[214:217], v[26:29]
	v_mfma_f32_16x16x32_bf16 v[18:21], v[184:187], v[222:225], v[18:21]
	v_mfma_f32_16x16x32_bf16 v[10:13], v[192:195], v[222:225], v[10:13]
	v_mfma_f32_16x16x32_bf16 v[6:9], v[184:187], v[230:233], v[6:9]
	v_mfma_f32_16x16x32_bf16 v[2:5], v[192:195], v[230:233], v[2:5]
	s_barrier
	s_add_i32 s51, s51, 2
	s_add_u32 s49, s49, 0x100
	s_addc_u32 s50, s50, 0
	s_cmp_gt_u32 s51, 29
	s_cbranch_scc0 .LBB0_169
	s_setprio 0
	s_and_b64 vcc, exec, s[8:9]
	s_cbranch_vccz .LBB0_172
	s_barrier

.LBB0_516:
	s_add_u32 s46, s44, 0xfff80080
	s_addc_u32 s47, s45, -1
	s_add_i32 s58, 0, 0x10000
	s_cmp_eq_u32 s57, 28
	s_cselect_b32 s49, s21, s47
	s_cselect_b32 s48, s50, s46
	s_cselect_b32 s47, s13, s56
	s_cselect_b32 s46, s51, s55
	ds_read_b128 v[82:85], v236
	ds_read_b128 v[86:89], v236 offset:1024
	ds_read_b128 v[98:101], v236 offset:2048
	ds_read_b128 v[102:105], v236 offset:3072
	ds_read_b128 v[154:157], v237
	ds_read_b128 v[168:171], v237 offset:1024
	ds_read_b128 v[176:179], v237 offset:2048
	ds_read_b128 v[180:183], v237 offset:3072
	s_add_i32 m0, s14, 0xc000
	ds_read_b128 v[184:187], v174
	ds_read_b128 v[188:191], v174 offset:1024
	ds_read_b128 v[192:195], v174 offset:2048
	ds_read_b128 v[196:199], v174 offset:3072
	ds_read_b128 v[200:203], v174 offset:4096
	ds_read_b128 v[210:213], v174 offset:5120
	ds_read_b128 v[214:217], v174 offset:6144
	ds_read_b128 v[218:221], v174 offset:7168
	global_load_lds_dwordx4 v164, s[44:45]
	s_add_i32 m0, s14, 0xe000
	s_add_i32 s60, 0, 0x14000
	global_load_lds_dwordx4 v166, s[44:45]
	s_waitcnt vmcnt(8) lgkmcnt(0)
	s_barrier
	v_mfma_f32_16x16x32_bf16 v[142:145], v[82:85], v[184:187], v[142:145]
	v_mfma_f32_16x16x32_bf16 v[138:141], v[98:101], v[184:187], v[138:141]
	v_mfma_f32_16x16x32_bf16 v[126:129], v[82:85], v[192:195], v[126:129]
	v_mfma_f32_16x16x32_bf16 v[122:125], v[98:101], v[192:195], v[122:125]
	v_mfma_f32_16x16x32_bf16 v[110:113], v[82:85], v[200:203], v[110:113]
	v_mfma_f32_16x16x32_bf16 v[106:109], v[98:101], v[200:203], v[106:109]
	v_mfma_f32_16x16x32_bf16 v[78:81], v[82:85], v[214:217], v[78:81]
	v_mfma_f32_16x16x32_bf16 v[74:77], v[98:101], v[214:217], v[74:77]
	v_mfma_f32_16x16x32_bf16 v[142:145], v[86:89], v[188:191], v[142:145]
	v_mfma_f32_16x16x32_bf16 v[138:141], v[102:105], v[188:191], v[138:141]
	v_mfma_f32_16x16x32_bf16 v[126:129], v[86:89], v[196:199], v[126:129]
	v_mfma_f32_16x16x32_bf16 v[122:125], v[102:105], v[196:199], v[122:125]
	v_mfma_f32_16x16x32_bf16 v[110:113], v[86:89], v[210:213], v[110:113]
	v_mfma_f32_16x16x32_bf16 v[106:109], v[102:105], v[210:213], v[106:109]
	v_mfma_f32_16x16x32_bf16 v[78:81], v[86:89], v[218:221], v[78:81]
	v_mfma_f32_16x16x32_bf16 v[74:77], v[102:105], v[218:221], v[74:77]
	v_mfma_f32_16x16x32_bf16 v[134:137], v[154:157], v[184:187], v[134:137]
	v_mfma_f32_16x16x32_bf16 v[130:133], v[176:179], v[184:187], v[130:133]
	v_mfma_f32_16x16x32_bf16 v[118:121], v[154:157], v[192:195], v[118:121]
	v_mfma_f32_16x16x32_bf16 v[114:117], v[176:179], v[192:195], v[114:117]
	v_mfma_f32_16x16x32_bf16 v[94:97], v[154:157], v[200:203], v[94:97]
	v_mfma_f32_16x16x32_bf16 v[90:93], v[176:179], v[200:203], v[90:93]
	v_mfma_f32_16x16x32_bf16 v[70:73], v[154:157], v[214:217], v[70:73]
	v_mfma_f32_16x16x32_bf16 v[66:69], v[176:179], v[214:217], v[66:69]
	v_mfma_f32_16x16x32_bf16 v[134:137], v[168:171], v[188:191], v[134:137]
	v_mfma_f32_16x16x32_bf16 v[130:133], v[180:183], v[188:191], v[130:133]
	v_mfma_f32_16x16x32_bf16 v[118:121], v[168:171], v[196:199], v[118:121]
	v_mfma_f32_16x16x32_bf16 v[114:117], v[180:183], v[196:199], v[114:117]
	v_mfma_f32_16x16x32_bf16 v[94:97], v[168:171], v[210:213], v[94:97]
	v_mfma_f32_16x16x32_bf16 v[90:93], v[180:183], v[210:213], v[90:93]
	v_mfma_f32_16x16x32_bf16 v[70:73], v[168:171], v[218:221], v[70:73]
	v_mfma_f32_16x16x32_bf16 v[66:69], v[180:183], v[218:221], v[66:69]
	s_barrier
	s_add_i32 s58, s58, s5
	s_mov_b32 m0, s58
	ds_read_b128 v[184:187], v174 offset:16384
	ds_read_b128 v[188:191], v174 offset:17408
	ds_read_b128 v[192:195], v174 offset:18432
	ds_read_b128 v[196:199], v174 offset:19456
	ds_read_b128 v[200:203], v174 offset:20480
	ds_read_b128 v[210:213], v174 offset:21504
	ds_read_b128 v[214:217], v174 offset:22528
	ds_read_b128 v[218:221], v174 offset:23552
	global_load_lds_dwordx4 v0, s[46:47]
	s_add_i32 m0, s58, 0x2000
	s_add_i32 s60, s60, s5
	global_load_lds_dwordx4 v158, s[46:47]
	s_mov_b32 m0, s60
	s_add_u32 s58, s46, 0x80000
	s_addc_u32 s59, s47, 0
	global_load_lds_dwordx4 v0, s[58:59]
	s_add_i32 m0, s60, 0x2000
	s_add_u32 s100, s48, 0x80
	global_load_lds_dwordx4 v158, s[58:59]
	s_addc_u32 s101, s49, 0
	s_mov_b32 m0, s14
	s_add_u32 s98, s46, 0x80
	global_load_lds_dwordx4 v162, s[48:49]
	s_mov_b32 m0, s15
	s_addc_u32 s99, s47, 0
	global_load_lds_dwordx4 v160, s[48:49]
	s_waitcnt vmcnt(8) lgkmcnt(0)
	s_barrier
	v_mfma_f32_16x16x32_bf16 v[62:65], v[82:85], v[184:187], v[62:65]
	v_mfma_f32_16x16x32_bf16 v[58:61], v[98:101], v[184:187], v[58:61]
	v_mfma_f32_16x16x32_bf16 v[46:49], v[82:85], v[192:195], v[46:49]
	v_mfma_f32_16x16x32_bf16 v[42:45], v[98:101], v[192:195], v[42:45]
	v_mfma_f32_16x16x32_bf16 v[30:33], v[82:85], v[200:203], v[30:33]
	v_mfma_f32_16x16x32_bf16 v[26:29], v[98:101], v[200:203], v[26:29]
	v_mfma_f32_16x16x32_bf16 v[14:17], v[82:85], v[214:217], v[14:17]
	v_mfma_f32_16x16x32_bf16 v[10:13], v[98:101], v[214:217], v[10:13]
	v_mfma_f32_16x16x32_bf16 v[62:65], v[86:89], v[188:191], v[62:65]
	v_mfma_f32_16x16x32_bf16 v[58:61], v[102:105], v[188:191], v[58:61]
	v_mfma_f32_16x16x32_bf16 v[46:49], v[86:89], v[196:199], v[46:49]
	v_mfma_f32_16x16x32_bf16 v[42:45], v[102:105], v[196:199], v[42:45]
	v_mfma_f32_16x16x32_bf16 v[30:33], v[86:89], v[210:213], v[30:33]
	v_mfma_f32_16x16x32_bf16 v[26:29], v[102:105], v[210:213], v[26:29]
	v_mfma_f32_16x16x32_bf16 v[14:17], v[86:89], v[218:221], v[14:17]
	v_mfma_f32_16x16x32_bf16 v[10:13], v[102:105], v[218:221], v[10:13]
	v_mfma_f32_16x16x32_bf16 v[54:57], v[154:157], v[184:187], v[54:57]
	v_mfma_f32_16x16x32_bf16 v[50:53], v[176:179], v[184:187], v[50:53]
	v_mfma_f32_16x16x32_bf16 v[38:41], v[154:157], v[192:195], v[38:41]
	v_mfma_f32_16x16x32_bf16 v[34:37], v[176:179], v[192:195], v[34:37]
	v_mfma_f32_16x16x32_bf16 v[22:25], v[154:157], v[200:203], v[22:25]
	v_mfma_f32_16x16x32_bf16 v[18:21], v[176:179], v[200:203], v[18:21]
	v_mfma_f32_16x16x32_bf16 v[6:9], v[154:157], v[214:217], v[6:9]
	v_mfma_f32_16x16x32_bf16 v[2:5], v[176:179], v[214:217], v[2:5]
	v_mfma_f32_16x16x32_bf16 v[54:57], v[168:171], v[188:191], v[54:57]
	v_mfma_f32_16x16x32_bf16 v[50:53], v[180:183], v[188:191], v[50:53]
	v_mfma_f32_16x16x32_bf16 v[38:41], v[168:171], v[196:199], v[38:41]
	v_mfma_f32_16x16x32_bf16 v[34:37], v[180:183], v[196:199], v[34:37]
	v_mfma_f32_16x16x32_bf16 v[22:25], v[168:171], v[210:213], v[22:25]
	v_mfma_f32_16x16x32_bf16 v[18:21], v[180:183], v[210:213], v[18:21]
	v_mfma_f32_16x16x32_bf16 v[6:9], v[168:171], v[218:221], v[6:9]
	v_mfma_f32_16x16x32_bf16 v[2:5], v[180:183], v[218:221], v[2:5]
	s_barrier
	s_add_i32 s58, 0, 0x18000
	ds_read_b128 v[82:85], v238
	ds_read_b128 v[86:89], v238 offset:1024
	ds_read_b128 v[98:101], v238 offset:2048
	ds_read_b128 v[102:105], v238 offset:3072
	ds_read_b128 v[154:157], v239
	ds_read_b128 v[168:171], v239 offset:1024
	ds_read_b128 v[176:179], v239 offset:2048
	ds_read_b128 v[180:183], v239 offset:3072
	s_add_u32 s48, s48, 0x80000
	s_addc_u32 s49, s49, 0
	s_mov_b32 m0, s16
	ds_read_b128 v[184:187], v174 offset:32768
	ds_read_b128 v[188:191], v174 offset:33792
	ds_read_b128 v[192:195], v174 offset:34816
	ds_read_b128 v[196:199], v174 offset:35840
	ds_read_b128 v[200:203], v174 offset:36864
	ds_read_b128 v[210:213], v174 offset:37888
	ds_read_b128 v[214:217], v174 offset:38912
	ds_read_b128 v[218:221], v174 offset:39936
	global_load_lds_dwordx4 v162, s[48:49]
	s_mov_b32 m0, s18
	s_add_i32 s59, 0, 0x1c000
	global_load_lds_dwordx4 v160, s[48:49]
	s_waitcnt vmcnt(8) lgkmcnt(0)
	s_barrier
	v_mfma_f32_16x16x32_bf16 v[142:145], v[82:85], v[184:187], v[142:145]
	v_mfma_f32_16x16x32_bf16 v[138:141], v[98:101], v[184:187], v[138:141]
	v_mfma_f32_16x16x32_bf16 v[126:129], v[82:85], v[192:195], v[126:129]
	v_mfma_f32_16x16x32_bf16 v[122:125], v[98:101], v[192:195], v[122:125]
	v_mfma_f32_16x16x32_bf16 v[110:113], v[82:85], v[200:203], v[110:113]
	v_mfma_f32_16x16x32_bf16 v[106:109], v[98:101], v[200:203], v[106:109]
	v_mfma_f32_16x16x32_bf16 v[78:81], v[82:85], v[214:217], v[78:81]
	v_mfma_f32_16x16x32_bf16 v[74:77], v[98:101], v[214:217], v[74:77]
	v_mfma_f32_16x16x32_bf16 v[142:145], v[86:89], v[188:191], v[142:145]
	v_mfma_f32_16x16x32_bf16 v[138:141], v[102:105], v[188:191], v[138:141]
	v_mfma_f32_16x16x32_bf16 v[126:129], v[86:89], v[196:199], v[126:129]
	v_mfma_f32_16x16x32_bf16 v[122:125], v[102:105], v[196:199], v[122:125]
	v_mfma_f32_16x16x32_bf16 v[110:113], v[86:89], v[210:213], v[110:113]
	v_mfma_f32_16x16x32_bf16 v[106:109], v[102:105], v[210:213], v[106:109]
	v_mfma_f32_16x16x32_bf16 v[78:81], v[86:89], v[218:221], v[78:81]
	v_mfma_f32_16x16x32_bf16 v[74:77], v[102:105], v[218:221], v[74:77]
	v_mfma_f32_16x16x32_bf16 v[134:137], v[154:157], v[184:187], v[134:137]
	v_mfma_f32_16x16x32_bf16 v[130:133], v[176:179], v[184:187], v[130:133]
	v_mfma_f32_16x16x32_bf16 v[118:121], v[154:157], v[192:195], v[118:121]
	v_mfma_f32_16x16x32_bf16 v[114:117], v[176:179], v[192:195], v[114:117]
	v_mfma_f32_16x16x32_bf16 v[94:97], v[154:157], v[200:203], v[94:97]
	v_mfma_f32_16x16x32_bf16 v[90:93], v[176:179], v[200:203], v[90:93]
	v_mfma_f32_16x16x32_bf16 v[70:73], v[154:157], v[214:217], v[70:73]
	v_mfma_f32_16x16x32_bf16 v[66:69], v[176:179], v[214:217], v[66:69]
	v_mfma_f32_16x16x32_bf16 v[134:137], v[168:171], v[188:191], v[134:137]
	v_mfma_f32_16x16x32_bf16 v[130:133], v[180:183], v[188:191], v[130:133]
	v_mfma_f32_16x16x32_bf16 v[118:121], v[168:171], v[196:199], v[118:121]
	v_mfma_f32_16x16x32_bf16 v[114:117], v[180:183], v[196:199], v[114:117]
	v_mfma_f32_16x16x32_bf16 v[94:97], v[168:171], v[210:213], v[94:97]
	v_mfma_f32_16x16x32_bf16 v[90:93], v[180:183], v[210:213], v[90:93]
	v_mfma_f32_16x16x32_bf16 v[70:73], v[168:171], v[218:221], v[70:73]
	v_mfma_f32_16x16x32_bf16 v[66:69], v[180:183], v[218:221], v[66:69]
	s_barrier
	s_add_i32 s48, s58, s5
	s_mov_b32 m0, s48
	ds_read_b128 v[184:187], v174 offset:49152
	ds_read_b128 v[188:191], v174 offset:50176
	ds_read_b128 v[192:195], v174 offset:51200
	ds_read_b128 v[196:199], v174 offset:52224
	ds_read_b128 v[200:203], v174 offset:53248
	ds_read_b128 v[210:213], v174 offset:54272
	ds_read_b128 v[214:217], v174 offset:55296
	ds_read_b128 v[218:221], v174 offset:56320
	global_load_lds_dwordx4 v0, s[98:99]
	s_add_i32 m0, s48, 0x2000
	s_add_i32 s48, s59, s5
	global_load_lds_dwordx4 v158, s[98:99]
	s_mov_b32 m0, s48
	s_add_u32 s46, s46, 0x80080
	s_addc_u32 s47, s47, 0
	global_load_lds_dwordx4 v0, s[46:47]
	s_add_i32 m0, s48, 0x2000
	s_nop 0
	global_load_lds_dwordx4 v158, s[46:47]
	s_mov_b32 m0, s25
	s_add_u32 s44, s44, 0x100
	global_load_lds_dwordx4 v162, s[100:101]
	s_mov_b32 m0, s33
	s_addc_u32 s45, s45, 0
	global_load_lds_dwordx4 v160, s[100:101]
	s_waitcnt vmcnt(8) lgkmcnt(0)
	s_barrier
	v_mfma_f32_16x16x32_bf16 v[62:65], v[82:85], v[184:187], v[62:65]
	v_mfma_f32_16x16x32_bf16 v[58:61], v[98:101], v[184:187], v[58:61]
	v_mfma_f32_16x16x32_bf16 v[46:49], v[82:85], v[192:195], v[46:49]
	v_mfma_f32_16x16x32_bf16 v[42:45], v[98:101], v[192:195], v[42:45]
	v_mfma_f32_16x16x32_bf16 v[30:33], v[82:85], v[200:203], v[30:33]
	v_mfma_f32_16x16x32_bf16 v[26:29], v[98:101], v[200:203], v[26:29]
	v_mfma_f32_16x16x32_bf16 v[14:17], v[82:85], v[214:217], v[14:17]
	v_mfma_f32_16x16x32_bf16 v[10:13], v[98:101], v[214:217], v[10:13]
	v_mfma_f32_16x16x32_bf16 v[62:65], v[86:89], v[188:191], v[62:65]
	v_mfma_f32_16x16x32_bf16 v[58:61], v[102:105], v[188:191], v[58:61]
	v_mfma_f32_16x16x32_bf16 v[46:49], v[86:89], v[196:199], v[46:49]
	v_mfma_f32_16x16x32_bf16 v[42:45], v[102:105], v[196:199], v[42:45]
	v_mfma_f32_16x16x32_bf16 v[30:33], v[86:89], v[210:213], v[30:33]
	v_mfma_f32_16x16x32_bf16 v[26:29], v[102:105], v[210:213], v[26:29]
	v_mfma_f32_16x16x32_bf16 v[14:17], v[86:89], v[218:221], v[14:17]
	v_mfma_f32_16x16x32_bf16 v[10:13], v[102:105], v[218:221], v[10:13]
	v_mfma_f32_16x16x32_bf16 v[54:57], v[154:157], v[184:187], v[54:57]
	v_mfma_f32_16x16x32_bf16 v[50:53], v[176:179], v[184:187], v[50:53]
	v_mfma_f32_16x16x32_bf16 v[38:41], v[154:157], v[192:195], v[38:41]
	v_mfma_f32_16x16x32_bf16 v[34:37], v[176:179], v[192:195], v[34:37]
	v_mfma_f32_16x16x32_bf16 v[22:25], v[154:157], v[200:203], v[22:25]
	v_mfma_f32_16x16x32_bf16 v[18:21], v[176:179], v[200:203], v[18:21]
	v_mfma_f32_16x16x32_bf16 v[6:9], v[154:157], v[214:217], v[6:9]
	v_mfma_f32_16x16x32_bf16 v[2:5], v[176:179], v[214:217], v[2:5]
	v_mfma_f32_16x16x32_bf16 v[54:57], v[168:171], v[188:191], v[54:57]
	v_mfma_f32_16x16x32_bf16 v[50:53], v[180:183], v[188:191], v[50:53]
	v_mfma_f32_16x16x32_bf16 v[38:41], v[168:171], v[196:199], v[38:41]
	v_mfma_f32_16x16x32_bf16 v[34:37], v[180:183], v[196:199], v[34:37]
	v_mfma_f32_16x16x32_bf16 v[22:25], v[168:171], v[210:213], v[22:25]
	v_mfma_f32_16x16x32_bf16 v[18:21], v[180:183], v[210:213], v[18:21]
	v_mfma_f32_16x16x32_bf16 v[6:9], v[168:171], v[218:221], v[6:9]
	v_mfma_f32_16x16x32_bf16 v[2:5], v[180:183], v[218:221], v[2:5]
	s_barrier
	s_add_i32 s57, s57, 2
	s_add_u32 s55, s55, 0x100
	s_addc_u32 s56, s56, 0
	s_cmp_gt_u32 s57, 29
	s_cbranch_scc0 .LBB0_516
	s_setprio 0
	s_and_b64 vcc, exec, s[10:11]
	s_cbranch_vccz .LBB0_519
	s_barrier

.LBB0_604:
	s_add_u32 s22, s6, 0xfff80080
	s_addc_u32 s23, s7, -1
	s_add_i32 s54, 0, 0x10000
	s_cmp_eq_u32 s53, 28
	s_cselect_b32 s47, s18, s23
	s_cselect_b32 s46, s19, s22
	s_cselect_b32 s23, s21, s52
	s_cselect_b32 s22, s25, s41
	ds_read_b128 v[130:133], v236
	ds_read_b128 v[134:137], v236 offset:1024
	ds_read_b128 v[154:157], v236 offset:2048
	ds_read_b128 v[162:165], v236 offset:3072
	ds_read_b128 v[166:169], v237
	ds_read_b128 v[170:173], v237 offset:1024
	ds_read_b128 v[180:183], v237 offset:2048
	ds_read_b128 v[184:187], v237 offset:3072
	s_add_i32 m0, s16, 0xc000
	ds_read_b128 v[188:191], v179
	ds_read_b128 v[192:195], v179 offset:1024
	ds_read_b128 v[196:199], v179 offset:2048
	ds_read_b128 v[200:203], v179 offset:3072
	ds_read_b128 v[210:213], v179 offset:4096
	ds_read_b128 v[214:217], v179 offset:5120
	ds_read_b128 v[218:221], v179 offset:6144
	ds_read_b128 v[222:225], v179 offset:7168
	global_load_lds_dwordx4 v158, s[6:7]
	s_add_i32 m0, s16, 0xe000
	s_add_i32 s56, 0, 0x14000
	global_load_lds_dwordx4 v160, s[6:7]
	s_waitcnt vmcnt(8) lgkmcnt(0)
	s_barrier
	v_mfma_f32_16x16x32_bf16 v[126:129], v[130:133], v[188:191], v[126:129]
	v_mfma_f32_16x16x32_bf16 v[122:125], v[154:157], v[188:191], v[122:125]
	v_mfma_f32_16x16x32_bf16 v[110:113], v[130:133], v[196:199], v[110:113]
	v_mfma_f32_16x16x32_bf16 v[106:109], v[154:157], v[196:199], v[106:109]
	v_mfma_f32_16x16x32_bf16 v[94:97], v[130:133], v[210:213], v[94:97]
	v_mfma_f32_16x16x32_bf16 v[90:93], v[154:157], v[210:213], v[90:93]
	v_mfma_f32_16x16x32_bf16 v[78:81], v[130:133], v[218:221], v[78:81]
	v_mfma_f32_16x16x32_bf16 v[74:77], v[154:157], v[218:221], v[74:77]
	v_mfma_f32_16x16x32_bf16 v[126:129], v[134:137], v[192:195], v[126:129]
	v_mfma_f32_16x16x32_bf16 v[122:125], v[162:165], v[192:195], v[122:125]
	v_mfma_f32_16x16x32_bf16 v[110:113], v[134:137], v[200:203], v[110:113]
	v_mfma_f32_16x16x32_bf16 v[106:109], v[162:165], v[200:203], v[106:109]
	v_mfma_f32_16x16x32_bf16 v[94:97], v[134:137], v[214:217], v[94:97]
	v_mfma_f32_16x16x32_bf16 v[90:93], v[162:165], v[214:217], v[90:93]
	v_mfma_f32_16x16x32_bf16 v[78:81], v[134:137], v[222:225], v[78:81]
	v_mfma_f32_16x16x32_bf16 v[74:77], v[162:165], v[222:225], v[74:77]
	v_mfma_f32_16x16x32_bf16 v[118:121], v[166:169], v[188:191], v[118:121]
	v_mfma_f32_16x16x32_bf16 v[114:117], v[180:183], v[188:191], v[114:117]
	v_mfma_f32_16x16x32_bf16 v[102:105], v[166:169], v[196:199], v[102:105]
	v_mfma_f32_16x16x32_bf16 v[98:101], v[180:183], v[196:199], v[98:101]
	v_mfma_f32_16x16x32_bf16 v[86:89], v[166:169], v[210:213], v[86:89]
	v_mfma_f32_16x16x32_bf16 v[82:85], v[180:183], v[210:213], v[82:85]
	v_mfma_f32_16x16x32_bf16 v[70:73], v[166:169], v[218:221], v[70:73]
	v_mfma_f32_16x16x32_bf16 v[66:69], v[180:183], v[218:221], v[66:69]
	v_mfma_f32_16x16x32_bf16 v[118:121], v[170:173], v[192:195], v[118:121]
	v_mfma_f32_16x16x32_bf16 v[114:117], v[184:187], v[192:195], v[114:117]
	v_mfma_f32_16x16x32_bf16 v[102:105], v[170:173], v[200:203], v[102:105]
	v_mfma_f32_16x16x32_bf16 v[98:101], v[184:187], v[200:203], v[98:101]
	v_mfma_f32_16x16x32_bf16 v[86:89], v[170:173], v[214:217], v[86:89]
	v_mfma_f32_16x16x32_bf16 v[82:85], v[184:187], v[214:217], v[82:85]
	v_mfma_f32_16x16x32_bf16 v[70:73], v[170:173], v[222:225], v[70:73]
	v_mfma_f32_16x16x32_bf16 v[66:69], v[184:187], v[222:225], v[66:69]
	s_barrier
	s_add_i32 s54, s54, s15
	s_mov_b32 m0, s54
	ds_read_b128 v[188:191], v179 offset:16384
	ds_read_b128 v[192:195], v179 offset:17408
	ds_read_b128 v[196:199], v179 offset:18432
	ds_read_b128 v[200:203], v179 offset:19456
	ds_read_b128 v[210:213], v179 offset:20480
	ds_read_b128 v[214:217], v179 offset:21504
	ds_read_b128 v[218:221], v179 offset:22528
	ds_read_b128 v[222:225], v179 offset:23552
	global_load_lds_dwordx4 v142, s[22:23]
	s_add_i32 m0, s54, 0x2000
	s_add_i32 s56, s56, s15
	global_load_lds_dwordx4 v138, s[22:23]
	s_mov_b32 m0, s56
	s_add_u32 s54, s22, 0x80000
	s_addc_u32 s55, s23, 0
	global_load_lds_dwordx4 v142, s[54:55]
	s_add_i32 m0, s56, 0x2000
	s_add_u32 s100, s46, 0x80
	global_load_lds_dwordx4 v138, s[54:55]
	s_addc_u32 s101, s47, 0
	s_mov_b32 m0, s16
	s_add_u32 s98, s22, 0x80
	global_load_lds_dwordx4 v144, s[46:47]
	s_mov_b32 m0, s33
	s_addc_u32 s99, s23, 0
	global_load_lds_dwordx4 v140, s[46:47]
	s_waitcnt vmcnt(8) lgkmcnt(0)
	s_barrier
	v_mfma_f32_16x16x32_bf16 v[62:65], v[130:133], v[188:191], v[62:65]
	v_mfma_f32_16x16x32_bf16 v[58:61], v[154:157], v[188:191], v[58:61]
	v_mfma_f32_16x16x32_bf16 v[46:49], v[130:133], v[196:199], v[46:49]
	v_mfma_f32_16x16x32_bf16 v[42:45], v[154:157], v[196:199], v[42:45]
	v_mfma_f32_16x16x32_bf16 v[30:33], v[130:133], v[210:213], v[30:33]
	v_mfma_f32_16x16x32_bf16 v[26:29], v[154:157], v[210:213], v[26:29]
	v_mfma_f32_16x16x32_bf16 v[14:17], v[130:133], v[218:221], v[14:17]
	v_mfma_f32_16x16x32_bf16 v[10:13], v[154:157], v[218:221], v[10:13]
	v_mfma_f32_16x16x32_bf16 v[62:65], v[134:137], v[192:195], v[62:65]
	v_mfma_f32_16x16x32_bf16 v[58:61], v[162:165], v[192:195], v[58:61]
	v_mfma_f32_16x16x32_bf16 v[46:49], v[134:137], v[200:203], v[46:49]
	v_mfma_f32_16x16x32_bf16 v[42:45], v[162:165], v[200:203], v[42:45]
	v_mfma_f32_16x16x32_bf16 v[30:33], v[134:137], v[214:217], v[30:33]
	v_mfma_f32_16x16x32_bf16 v[26:29], v[162:165], v[214:217], v[26:29]
	v_mfma_f32_16x16x32_bf16 v[14:17], v[134:137], v[222:225], v[14:17]
	v_mfma_f32_16x16x32_bf16 v[10:13], v[162:165], v[222:225], v[10:13]
	v_mfma_f32_16x16x32_bf16 v[54:57], v[166:169], v[188:191], v[54:57]
	v_mfma_f32_16x16x32_bf16 v[50:53], v[180:183], v[188:191], v[50:53]
	v_mfma_f32_16x16x32_bf16 v[38:41], v[166:169], v[196:199], v[38:41]
	v_mfma_f32_16x16x32_bf16 v[34:37], v[180:183], v[196:199], v[34:37]
	v_mfma_f32_16x16x32_bf16 v[22:25], v[166:169], v[210:213], v[22:25]
	v_mfma_f32_16x16x32_bf16 v[18:21], v[180:183], v[210:213], v[18:21]
	v_mfma_f32_16x16x32_bf16 v[6:9], v[166:169], v[218:221], v[6:9]
	v_mfma_f32_16x16x32_bf16 v[2:5], v[180:183], v[218:221], v[2:5]
	v_mfma_f32_16x16x32_bf16 v[54:57], v[170:173], v[192:195], v[54:57]
	v_mfma_f32_16x16x32_bf16 v[50:53], v[184:187], v[192:195], v[50:53]
	v_mfma_f32_16x16x32_bf16 v[38:41], v[170:173], v[200:203], v[38:41]
	v_mfma_f32_16x16x32_bf16 v[34:37], v[184:187], v[200:203], v[34:37]
	v_mfma_f32_16x16x32_bf16 v[22:25], v[170:173], v[214:217], v[22:25]
	v_mfma_f32_16x16x32_bf16 v[18:21], v[184:187], v[214:217], v[18:21]
	v_mfma_f32_16x16x32_bf16 v[6:9], v[170:173], v[222:225], v[6:9]
	v_mfma_f32_16x16x32_bf16 v[2:5], v[184:187], v[222:225], v[2:5]
	s_barrier
	s_add_i32 s54, 0, 0x18000
	ds_read_b128 v[130:133], v238
	ds_read_b128 v[134:137], v238 offset:1024
	ds_read_b128 v[154:157], v238 offset:2048
	ds_read_b128 v[162:165], v238 offset:3072
	ds_read_b128 v[166:169], v239
	ds_read_b128 v[170:173], v239 offset:1024
	ds_read_b128 v[180:183], v239 offset:2048
	ds_read_b128 v[184:187], v239 offset:3072
	s_add_u32 s46, s46, 0x80000
	s_addc_u32 s47, s47, 0
	s_mov_b32 m0, s37
	ds_read_b128 v[188:191], v179 offset:32768
	ds_read_b128 v[192:195], v179 offset:33792
	ds_read_b128 v[196:199], v179 offset:34816
	ds_read_b128 v[200:203], v179 offset:35840
	ds_read_b128 v[210:213], v179 offset:36864
	ds_read_b128 v[214:217], v179 offset:37888
	ds_read_b128 v[218:221], v179 offset:38912
	ds_read_b128 v[222:225], v179 offset:39936
	global_load_lds_dwordx4 v144, s[46:47]
	s_mov_b32 m0, s48
	s_add_i32 s55, 0, 0x1c000
	global_load_lds_dwordx4 v140, s[46:47]
	s_waitcnt vmcnt(8) lgkmcnt(0)
	s_barrier
	v_mfma_f32_16x16x32_bf16 v[126:129], v[130:133], v[188:191], v[126:129]
	v_mfma_f32_16x16x32_bf16 v[122:125], v[154:157], v[188:191], v[122:125]
	v_mfma_f32_16x16x32_bf16 v[110:113], v[130:133], v[196:199], v[110:113]
	v_mfma_f32_16x16x32_bf16 v[106:109], v[154:157], v[196:199], v[106:109]
	v_mfma_f32_16x16x32_bf16 v[94:97], v[130:133], v[210:213], v[94:97]
	v_mfma_f32_16x16x32_bf16 v[90:93], v[154:157], v[210:213], v[90:93]
	v_mfma_f32_16x16x32_bf16 v[78:81], v[130:133], v[218:221], v[78:81]
	v_mfma_f32_16x16x32_bf16 v[74:77], v[154:157], v[218:221], v[74:77]
	v_mfma_f32_16x16x32_bf16 v[126:129], v[134:137], v[192:195], v[126:129]
	v_mfma_f32_16x16x32_bf16 v[122:125], v[162:165], v[192:195], v[122:125]
	v_mfma_f32_16x16x32_bf16 v[110:113], v[134:137], v[200:203], v[110:113]
	v_mfma_f32_16x16x32_bf16 v[106:109], v[162:165], v[200:203], v[106:109]
	v_mfma_f32_16x16x32_bf16 v[94:97], v[134:137], v[214:217], v[94:97]
	v_mfma_f32_16x16x32_bf16 v[90:93], v[162:165], v[214:217], v[90:93]
	v_mfma_f32_16x16x32_bf16 v[78:81], v[134:137], v[222:225], v[78:81]
	v_mfma_f32_16x16x32_bf16 v[74:77], v[162:165], v[222:225], v[74:77]
	v_mfma_f32_16x16x32_bf16 v[118:121], v[166:169], v[188:191], v[118:121]
	v_mfma_f32_16x16x32_bf16 v[114:117], v[180:183], v[188:191], v[114:117]
	v_mfma_f32_16x16x32_bf16 v[102:105], v[166:169], v[196:199], v[102:105]
	v_mfma_f32_16x16x32_bf16 v[98:101], v[180:183], v[196:199], v[98:101]
	v_mfma_f32_16x16x32_bf16 v[86:89], v[166:169], v[210:213], v[86:89]
	v_mfma_f32_16x16x32_bf16 v[82:85], v[180:183], v[210:213], v[82:85]
	v_mfma_f32_16x16x32_bf16 v[70:73], v[166:169], v[218:221], v[70:73]
	v_mfma_f32_16x16x32_bf16 v[66:69], v[180:183], v[218:221], v[66:69]
	v_mfma_f32_16x16x32_bf16 v[118:121], v[170:173], v[192:195], v[118:121]
	v_mfma_f32_16x16x32_bf16 v[114:117], v[184:187], v[192:195], v[114:117]
	v_mfma_f32_16x16x32_bf16 v[102:105], v[170:173], v[200:203], v[102:105]
	v_mfma_f32_16x16x32_bf16 v[98:101], v[184:187], v[200:203], v[98:101]
	v_mfma_f32_16x16x32_bf16 v[86:89], v[170:173], v[214:217], v[86:89]
	v_mfma_f32_16x16x32_bf16 v[82:85], v[184:187], v[214:217], v[82:85]
	v_mfma_f32_16x16x32_bf16 v[70:73], v[170:173], v[222:225], v[70:73]
	v_mfma_f32_16x16x32_bf16 v[66:69], v[184:187], v[222:225], v[66:69]
	s_barrier
	s_add_i32 s46, s54, s15
	s_mov_b32 m0, s46
	ds_read_b128 v[188:191], v179 offset:49152
	ds_read_b128 v[192:195], v179 offset:50176
	ds_read_b128 v[196:199], v179 offset:51200
	ds_read_b128 v[200:203], v179 offset:52224
	ds_read_b128 v[210:213], v179 offset:53248
	ds_read_b128 v[214:217], v179 offset:54272
	ds_read_b128 v[218:221], v179 offset:55296
	ds_read_b128 v[222:225], v179 offset:56320
	global_load_lds_dwordx4 v142, s[98:99]
	s_add_i32 m0, s46, 0x2000
	s_add_i32 s46, s55, s15
	global_load_lds_dwordx4 v138, s[98:99]
	s_mov_b32 m0, s46
	s_add_u32 s22, s22, 0x80080
	s_addc_u32 s23, s23, 0
	global_load_lds_dwordx4 v142, s[22:23]
	s_add_i32 m0, s46, 0x2000
	s_nop 0
	global_load_lds_dwordx4 v138, s[22:23]
	s_mov_b32 m0, s49
	s_add_u32 s6, s6, 0x100
	global_load_lds_dwordx4 v144, s[100:101]
	s_mov_b32 m0, s50
	s_addc_u32 s7, s7, 0
	global_load_lds_dwordx4 v140, s[100:101]
	s_waitcnt vmcnt(8) lgkmcnt(0)
	s_barrier
	v_mfma_f32_16x16x32_bf16 v[62:65], v[130:133], v[188:191], v[62:65]
	v_mfma_f32_16x16x32_bf16 v[58:61], v[154:157], v[188:191], v[58:61]
	v_mfma_f32_16x16x32_bf16 v[46:49], v[130:133], v[196:199], v[46:49]
	v_mfma_f32_16x16x32_bf16 v[42:45], v[154:157], v[196:199], v[42:45]
	v_mfma_f32_16x16x32_bf16 v[30:33], v[130:133], v[210:213], v[30:33]
	v_mfma_f32_16x16x32_bf16 v[26:29], v[154:157], v[210:213], v[26:29]
	v_mfma_f32_16x16x32_bf16 v[14:17], v[130:133], v[218:221], v[14:17]
	v_mfma_f32_16x16x32_bf16 v[10:13], v[154:157], v[218:221], v[10:13]
	v_mfma_f32_16x16x32_bf16 v[62:65], v[134:137], v[192:195], v[62:65]
	v_mfma_f32_16x16x32_bf16 v[58:61], v[162:165], v[192:195], v[58:61]
	v_mfma_f32_16x16x32_bf16 v[46:49], v[134:137], v[200:203], v[46:49]
	v_mfma_f32_16x16x32_bf16 v[42:45], v[162:165], v[200:203], v[42:45]
	v_mfma_f32_16x16x32_bf16 v[30:33], v[134:137], v[214:217], v[30:33]
	v_mfma_f32_16x16x32_bf16 v[26:29], v[162:165], v[214:217], v[26:29]
	v_mfma_f32_16x16x32_bf16 v[14:17], v[134:137], v[222:225], v[14:17]
	v_mfma_f32_16x16x32_bf16 v[10:13], v[162:165], v[222:225], v[10:13]
	v_mfma_f32_16x16x32_bf16 v[54:57], v[166:169], v[188:191], v[54:57]
	v_mfma_f32_16x16x32_bf16 v[50:53], v[180:183], v[188:191], v[50:53]
	v_mfma_f32_16x16x32_bf16 v[38:41], v[166:169], v[196:199], v[38:41]
	v_mfma_f32_16x16x32_bf16 v[34:37], v[180:183], v[196:199], v[34:37]
	v_mfma_f32_16x16x32_bf16 v[22:25], v[166:169], v[210:213], v[22:25]
	v_mfma_f32_16x16x32_bf16 v[18:21], v[180:183], v[210:213], v[18:21]
	v_mfma_f32_16x16x32_bf16 v[6:9], v[166:169], v[218:221], v[6:9]
	v_mfma_f32_16x16x32_bf16 v[2:5], v[180:183], v[218:221], v[2:5]
	v_mfma_f32_16x16x32_bf16 v[54:57], v[170:173], v[192:195], v[54:57]
	v_mfma_f32_16x16x32_bf16 v[50:53], v[184:187], v[192:195], v[50:53]
	v_mfma_f32_16x16x32_bf16 v[38:41], v[170:173], v[200:203], v[38:41]
	v_mfma_f32_16x16x32_bf16 v[34:37], v[184:187], v[200:203], v[34:37]
	v_mfma_f32_16x16x32_bf16 v[22:25], v[170:173], v[214:217], v[22:25]
	v_mfma_f32_16x16x32_bf16 v[18:21], v[184:187], v[214:217], v[18:21]
	v_mfma_f32_16x16x32_bf16 v[6:9], v[170:173], v[222:225], v[6:9]
	v_mfma_f32_16x16x32_bf16 v[2:5], v[184:187], v[222:225], v[2:5]
	s_barrier
	s_add_i32 s53, s53, 2
	s_add_u32 s41, s41, 0x100
	s_addc_u32 s52, s52, 0
	s_cmp_gt_u32 s53, 29
	s_cbranch_scc0 .LBB0_604
	s_setprio 0
	s_and_b64 vcc, exec, s[12:13]
	s_cbranch_vccz .LBB0_607
	s_barrier
